# PREP: fp8 conversion start rotated by 32 workgroups so the 7th item and the third ret_kv unit fall on different workgroups
# baseline (speedup 1.0000x reference)
; __device__ __forceinline__ unsigned xb_ld(unsigned* p)              { return __hip_atomic_load(p, __ATOMIC_RELAXED, __HIP_MEMORY_SCOPE_AGENT); }
; __device__ __forceinline__ void xcd_barrier_complete(unsigned* bar, unsigned x, unsigned& nloc, unsigned& nx) {
;     const unsigned G = gridDim.x * gridDim.y * gridDim.z;
;     unsigned sum, cnt, mine, sp = 0u;
;     for (;;) {
;         sum = 0u; cnt = 0u; mine = 0u;
; #pragma unroll
;         for (unsigned j = 0; j < 16; ++j) { const unsigned c = xb_ld(&bar[XB_XCNT(j)]); sum += c; cnt += (c > 0u) ? 1u : 0u; mine = (j == x) ? c : mine; }
;         if (sum == G) break;
;         __builtin_amdgcn_s_sleep(1);
;         if ((++sp & 255u) == 0u) { if (xb_ld(&bar[XB_TMO])) break; if (sp > XB_SPIN_CAP) { atomicAdd(&bar[XB_TMO], 1u); break; } }
;     }
;     nloc = mine > 0u ? mine : 1u; nx = cnt > 0u ? cnt : 1u;
; }
; __device__ __forceinline__ int xcd_remap(int L, int nwg) { const int q = nwg / NXCD, r = nwg % NXCD, xcd = L % NXCD, off = L / NXCD; return (xcd < r ? xcd * (q + 1) : r * (q + 1) + (xcd - r) * q) + off; }
;     __device__ __forceinline__ bool next(int i, Unit& u) const {
;         const int L = i * G + c; if (L >= nwg) return false;
;         const int wgid = xcd_remap(L, nwg);
;         const int nig = WGM * nN, gid = wgid / nig, fm = gid * WGM, gsz = (nM - fm) < WGM ? (nM - fm) : WGM;
;         u.pm = fm + ((wgid % nig) % gsz); u.pn = (wgid % nig) / gsz; u.e = 0; u.nvalid = 256; u.lrow0 = 0; return true;
;     }
.LBB0_532:
	s_cmpk_lt_i32 s80, 0x300
	s_cselect_b64 s[4:5], -1, 0
	s_ashr_i32 s3, s80, 31
	s_lshr_b32 s3, s3, 29
	s_add_i32 s3, s80, s3
	s_ashr_i32 s12, s3, 3
	s_and_b32 s3, s3, -8
	s_sub_i32 s13, s80, s3
	v_writelane_b32 v251, s4, 10
	s_lshl_b32 s3, s13, 5
	s_cmp_lt_i32 s13, 0
	v_writelane_b32 v251, s5, 11
	s_movk_i32 s4, 0x61
	s_cselect_b32 s4, s4, 0x60
	s_mul_i32 s4, s4, s13
	s_mul_i32 s5, s13, 33
	s_cselect_b32 s3, s5, s3
	s_add_i32 s4, s4, s12
	s_mul_hi_i32 s5, s4, 0x2aaaaaab
	s_lshr_b32 s6, s5, 31
	s_ashr_i32 s5, s5, 4
	s_add_i32 s5, s5, s6
	s_mul_i32 s6, s5, 0x60
	s_sub_i32 s6, s4, s6
	s_bfe_i32 s4, s6, 0x80000
	s_bfe_u32 s4, s4, 0x3000c
	s_add_i32 s7, s6, s4
	s_bfe_i32 s4, s7, 0x80000
	s_and_b32 s7, s7, 0xf8
	s_sub_i32 s6, s6, s7
	s_lshl_b32 s5, s5, 3
	s_sext_i32_i16 s8, s4
	s_sext_i32_i8 s6, s6
	s_add_i32 s14, s5, s6
	s_ashr_i32 s5, s8, 3
	v_writelane_b32 v251, s5, 12
	s_lshr_b32 s4, s8, 3
	v_readlane_b32 s8, v251, 0
	v_readlane_b32 s10, v251, 2
	v_readlane_b32 s11, v251, 3
	s_add_u32 s6, s10, 0x4200
	s_addc_u32 s7, s11, 0
	s_add_u32 s28, s10, 0x4400
	v_readlane_b32 s9, v251, 1
	v_writelane_b32 v251, s6, 13
	s_addc_u32 s29, s11, 0
	s_load_dwordx8 s[16:23], s[0:1], 0x78
	v_writelane_b32 v251, s7, 14
	s_add_u32 s6, s10, 0x4500
	s_addc_u32 s7, s11, 0
	v_writelane_b32 v251, s6, 15
	s_mov_b32 s35, 0
	v_mbcnt_lo_u32_b32 v1, -1, 0
	v_writelane_b32 v251, s7, 16
	s_add_u32 s6, s10, 0x4600
	s_addc_u32 s7, s11, 0
	v_writelane_b32 v251, s6, 17
	s_movk_i32 s70, 0x2000
	s_mov_b32 s71, 0x10000
	v_writelane_b32 v251, s7, 18
	s_add_u32 s6, s10, 0x4700
	s_addc_u32 s7, s11, 0
	v_writelane_b32 v251, s6, 19
	v_mov_b32_e32 v199, 0
	s_mov_b64 s[38:39], 0x100
	v_writelane_b32 v251, s7, 20
	s_add_u32 s6, s10, 0x4800
	s_addc_u32 s7, s11, 0
	v_writelane_b32 v251, s6, 21
	v_mov_b32_e32 v222, 1
	s_movk_i32 s77, 0x1000
	v_writelane_b32 v251, s7, 22
	s_add_u32 s6, s10, 0x4900
	s_addc_u32 s7, s11, 0
	v_writelane_b32 v251, s6, 23
	v_mov_b32_e32 v223, 0x3ca908c9
	s_brev_b32 s82, -2
	v_writelane_b32 v251, s7, 24
	s_add_u32 s6, s10, 0x4a00
	s_addc_u32 s7, s11, 0
	v_writelane_b32 v251, s6, 25
	s_mov_b32 s83, 0xbfb8aa3b
	s_mov_b32 s92, 0x42ce8ed0
	v_writelane_b32 v251, s7, 26
	s_add_u32 s6, s10, 0x4b00
	s_addc_u32 s7, s11, 0
	v_writelane_b32 v251, s6, 27
	s_mov_b32 s93, 0xc2b17218
	v_mov_b32_e32 v224, 0x2000
	v_writelane_b32 v251, s7, 28
	s_add_u32 s6, s10, 0x4c00
	s_addc_u32 s7, s11, 0
	v_writelane_b32 v251, s6, 29
	s_mov_b64 s[24:25], 0x4000
	v_mbcnt_hi_u32_b32 v225, -1, v1
	v_writelane_b32 v251, s7, 30
	s_add_u32 s6, s10, 0x4d00
	s_addc_u32 s7, s11, 0
	v_writelane_b32 v251, s6, 31
	v_mov_b32_e32 v226, 0x3727c5ac
	v_mov_b32_e32 v227, 0x260
	v_writelane_b32 v251, s7, 32
	s_add_u32 s6, s10, 0x4e00
	s_addc_u32 s7, s11, 0
	v_writelane_b32 v251, s6, 33
	s_mov_b64 s[94:95], 0x11000000
	v_mov_b32_e32 v228, 0x7f7f7f7f
	v_writelane_b32 v251, s7, 34
	s_add_u32 s6, s10, 0x4f00
	s_addc_u32 s7, s11, 0
	v_writelane_b32 v251, s6, 35
	v_mov_b32_e32 v229, 0x6f
	v_mov_b32_e32 v230, 0x7f800000
	v_writelane_b32 v251, s7, 36
	s_add_u32 s6, s10, 0x5000
	s_addc_u32 s7, s11, 0
	v_writelane_b32 v251, s6, 37
	v_mov_b32_e32 v231, 0x600
	v_mov_b32_e32 v232, 0x42000000
	v_writelane_b32 v251, s7, 38
	s_add_u32 s6, s10, 0x5100
	s_addc_u32 s7, s11, 0
	v_writelane_b32 v251, s6, 39
	v_mov_b32_e32 v233, 0x42800000
	v_mov_b32_e32 v234, 0xf149f2ca
	v_writelane_b32 v251, s7, 40
	s_add_u32 s6, s10, 0x5200
	s_addc_u32 s7, s11, 0
	v_writelane_b32 v251, s6, 41
	v_mov_b32_e32 v235, 0xce6e6b28
	v_mov_b32_e32 v236, 0x4e6e6b28
	v_writelane_b32 v251, s7, 42
	s_add_u32 s6, s10, 0x5300
	s_addc_u32 s7, s11, 0
	v_writelane_b32 v251, s6, 43
	s_cmp_eq_u32 s2, 15
	v_mov_b32_e32 v237, 0xff800000
	v_writelane_b32 v251, s7, 44
	s_cselect_b64 s[6:7], -1, 0
	v_writelane_b32 v251, s6, 45
	s_cmp_eq_u32 s2, 14
	v_mov_b32_e32 v238, 0x40e00000
	v_writelane_b32 v251, s7, 46
	s_cselect_b64 s[6:7], -1, 0
	v_writelane_b32 v251, s6, 47
	s_cmp_eq_u32 s2, 13
	s_mov_b32 s96, s35
	v_writelane_b32 v251, s7, 48
	s_cselect_b64 s[6:7], -1, 0
	v_writelane_b32 v251, s6, 49
	s_cmp_eq_u32 s2, 12
	s_nop 0
	v_writelane_b32 v251, s7, 50
	s_cselect_b64 s[6:7], -1, 0
	v_writelane_b32 v251, s6, 51
	s_cmp_eq_u32 s2, 11
	s_nop 0
	v_writelane_b32 v251, s7, 52
	s_cselect_b64 s[6:7], -1, 0
	v_writelane_b32 v251, s6, 53
	s_cmp_eq_u32 s2, 10
	s_nop 0
	v_writelane_b32 v251, s7, 54
	s_cselect_b64 s[6:7], -1, 0
	v_writelane_b32 v251, s6, 55
	s_cmp_eq_u32 s2, 9
	s_nop 0
	v_writelane_b32 v251, s7, 56
	s_cselect_b64 s[6:7], -1, 0
	v_writelane_b32 v251, s6, 57
	s_cmp_eq_u32 s2, 8
	s_nop 0
	v_writelane_b32 v251, s7, 58
	s_cselect_b64 s[6:7], -1, 0
	v_writelane_b32 v251, s6, 59
	s_cmp_eq_u32 s2, 7
	s_nop 0
	v_writelane_b32 v251, s7, 60
	s_cselect_b64 s[6:7], -1, 0
	v_writelane_b32 v251, s6, 61
	s_cmp_eq_u32 s2, 6
	s_nop 0
	v_writelane_b32 v251, s7, 62
	s_cselect_b64 s[6:7], -1, 0
	v_writelane_b32 v251, s6, 63
	s_cmp_eq_u32 s2, 5
	s_nop 0
	v_writelane_b32 v250, s7, 0
	s_cselect_b64 s[6:7], -1, 0
	v_writelane_b32 v250, s6, 1
	s_cmp_eq_u32 s2, 4
	s_nop 0
	v_writelane_b32 v250, s7, 2
	s_cselect_b64 s[6:7], -1, 0
	v_writelane_b32 v250, s6, 3
	s_cmp_eq_u32 s2, 3
	s_nop 0
	v_writelane_b32 v250, s7, 4
	s_cselect_b64 s[6:7], -1, 0
	v_writelane_b32 v250, s6, 5
	s_cmp_eq_u32 s2, 2
	s_nop 0
	v_writelane_b32 v250, s7, 6
	s_cselect_b64 s[6:7], -1, 0
	v_writelane_b32 v250, s6, 7
	s_cmp_eq_u32 s2, 1
	s_nop 0
	v_writelane_b32 v250, s7, 8
	s_cselect_b64 s[6:7], -1, 0
	v_writelane_b32 v250, s6, 9
	s_cmp_eq_u32 s2, 0
	s_nop 0
	v_writelane_b32 v250, s7, 10
	s_cselect_b64 s[6:7], -1, 0
	s_lshl_b32 s2, s2, 8
	s_add_u32 s2, s10, s2
	v_writelane_b32 v250, s6, 11
	s_addc_u32 s5, s11, 0
; __device__ __forceinline__ float w_qscale(float wmax) { return exp2f(floorf(log2f(128.f / fmaxf(wmax, 1e-30f)))); }
; __device__ __forceinline__ bool witem_decode(const Frame& F, int l, int it, WItem& t) {
;     constexpr int I_GU = 4 * 16, I_DN = 4 * 8, N_GU = NE * I_GU, N_DN = NE * I_DN;
;     const float* wmax = (const float*)((const unsigned*)(F.ws + WS_CTL) + CW_WMAX);
;     int r = it, nblk, item;
;     if (r < N_GU) { const int le = l * NE + r / I_GU; t.W = F.in[16] + (size_t)le * D * 2048; t.WT = (unsigned char*)(F.ws + WS_WGU) + (size_t)le * 2048 * D; t.N = 2048; t.map = 1; nblk = 16; item = r % I_GU; t.scale = w_qscale(wmax[l * 2 + 0]); }
;     else if ((r -= N_GU) < N_DN) { const int le = l * NE + r / I_DN; t.W = F.in[18] + (size_t)le * FF * D; t.WT = (unsigned char*)(F.ws + WS_WDN) + (size_t)le * D * FF; t.N = D; t.map = 3; nblk = 8; item = r % I_DN; t.scale = w_qscale(wmax[l * 2 + 1]); }
;     else return false;
;     t.k0 = 256 * (item / nblk); t.n0 = 128 * (item % nblk); return true;
; __device__ __forceinline__ void phase_prep(const Frame& F, int l) {
;     if (FAST_RET && FAST_NSA) {
;         const int first = F.G > 32 ? 16 : 0;
;         if (F.bid < first || first == 0) {
;             for (int u = F.bid; u < 16; u += F.G) { const int which = u >> 3, p0 = (u & 7) * 2, lw = l * 2 + which;
;                 RowCmp R{p0}; EpiCmp E{F.lds, (unsigned char*)F.ws, (const float*)(F.ws + WS_CB1) + lw * 128, (const bf16*)(F.ws + WS_CW2T) + (size_t)lw * 64 * 128, which, p0, F.wave};
;                 gemm_unit(F, (const bf16*)(F.ws + (which ? WS_NVC : WS_NKC)), R, (const bf16*)(F.ws + WS_CW1T) + (size_t)lw * 128 * 2048, E, 64, 2048); }
;             __syncthreads();
;         }
;         if (F.bid >= first) {
;             conv_tokens(F, l, first); for (int u = F.bid - first; u < NB * 4 * 16; u += F.G - first) ret_kv_unit(F, u); __syncthreads();
;             gates_tiles(F, l, first);
;             fp8_convert_range(F, l, F.bid - first, F.G - first, CONV_SPLIT);
	s_nop 0
	v_writelane_b32 v250, s7, 12
	s_add_u32 s6, s2, 0x5400
	s_addc_u32 s7, s5, 0
	v_writelane_b32 v250, s6, 13
	s_nop 1
	v_writelane_b32 v250, s7, 14
	s_add_u32 s6, s2, 0x6400
	s_addc_u32 s7, s5, 0
	v_writelane_b32 v250, s6, 15
	s_nop 1
	v_writelane_b32 v250, s7, 16
	s_add_u32 s6, s10, 0x7400
	s_addc_u32 s7, s11, 0
	v_writelane_b32 v250, s6, 17
	s_nop 1
	v_writelane_b32 v250, s7, 18
	s_add_u32 s6, s10, 0x7500
	s_addc_u32 s7, s11, 0
	v_writelane_b32 v250, s6, 19
	s_cmp_lt_i32 s81, 33
	s_nop 0
	v_writelane_b32 v250, s7, 20
	s_cselect_b64 s[6:7], -1, 0
	s_and_b64 s[8:9], s[6:7], exec
	s_cselect_b32 s10, 0, 16
	s_cselect_b32 s2, 0, -16
	s_cmp_ge_i32 s80, s10
	s_cselect_b64 s[8:9], -1, 0
	v_writelane_b32 v250, s8, 21
	s_cmp_lt_i32 s80, s10
	s_nop 0
	v_writelane_b32 v250, s9, 22
	s_cselect_b64 s[8:9], -1, 0
	s_or_b64 s[6:7], s[6:7], s[8:9]
	v_writelane_b32 v250, s6, 23
	s_cmp_lt_i32 s80, 16
	s_nop 0
	v_writelane_b32 v250, s7, 24
	s_cselect_b64 s[6:7], -1, 0
	v_writelane_b32 v250, s6, 25
	s_sub_i32 s5, s80, s10
	s_sub_i32 s74, s81, s10
	v_writelane_b32 v250, s7, 26
	s_lshl_b32 s6, s5, 3
	s_lshl_b32 s75, s74, 3
	s_cmpk_gt_i32 s5, 0x1ff
	v_writelane_b32 v250, s6, 27
	s_cselect_b64 s[6:7], -1, 0
	s_add_i32 s76, s2, s81
	v_writelane_b32 v250, s6, 28
	s_nop 0
	v_writelane_b32 v250, s5, 33
	s_cmpk_gt_i32 s74, 63
	s_cselect_b32 s2, 32, 0
	s_sub_i32 s5, s5, s2
	s_cmp_lt_i32 s5, 0
	s_cselect_b32 s2, s74, 0
	s_add_i32 s5, s5, s2
	s_cmpk_lt_i32 s5, 0x600
	s_nop 0
	v_writelane_b32 v250, s7, 29
	s_cselect_b64 s[6:7], -1, 0
	s_ashr_i32 s2, s5, 31
	s_lshr_b32 s2, s2, 26
	v_writelane_b32 v250, s6, 30
	s_add_i32 s2, s5, s2
	s_nop 0
	v_writelane_b32 v250, s7, 31
	s_ashr_i32 s6, s2, 6
	s_and_b32 s2, s2, 0xffc0
	v_writelane_b32 v250, s6, 32
	s_sub_i32 s2, s5, s2
	v_writelane_b32 v248, s5, 40
	s_bfe_i32 s5, s2, 0x80000
	s_bfe_u32 s5, s5, 0x4000b
	s_add_i32 s5, s2, s5
	s_bfe_i32 s6, s5, 0x80000
	s_sext_i32_i16 s6, s6
	s_and_b32 s5, s5, 0xf0
	s_lshl_b32 s6, s6, 4
	s_sub_i32 s2, s2, s5
	s_and_b32 s6, s6, 0xffffff00
	s_sext_i32_i8 s2, s2
	v_writelane_b32 v250, s6, 34
	s_lshl_b32 s6, s2, 7
	s_ashr_i32 s7, s6, 31
	v_writelane_b32 v250, s6, 35
	s_lshl_b32 s2, s74, 1
	s_nop 0
	v_writelane_b32 v250, s7, 36
	v_writelane_b32 v250, s2, 37
	s_mul_hi_i32 s2, s80, 0x55555556
	s_lshr_b32 s5, s2, 31
	s_add_i32 s2, s2, s5
	s_mul_i32 s2, s2, 3
	s_sub_i32 s2, s80, s2
	s_cmp_eq_u32 s2, 0
	s_cselect_b64 s[6:7], -1, 0
	v_writelane_b32 v250, s6, 38
	s_nop 1
	v_writelane_b32 v250, s7, 39
	s_add_i32 s6, s80, 0x600
	s_cmpk_lt_i32 s80, 0x600
	s_cselect_b64 s[8:9], -1, 0
	v_writelane_b32 v250, s8, 40
	s_cmpk_lt_i32 s80, 0x200
	s_nop 0
	v_writelane_b32 v250, s9, 41
	s_cselect_b64 s[8:9], -1, 0
	v_writelane_b32 v250, s8, 42
	s_cmpk_gt_i32 s80, 0x1ff
	s_nop 0
	v_writelane_b32 v250, s9, 43
	s_cselect_b64 s[8:9], -1, 0
	v_writelane_b32 v250, s8, 44
	s_add_i32 s5, s80, 0xfffffe00
	s_lshr_b32 s5, s5, 5
	v_writelane_b32 v250, s9, 45
	v_writelane_b32 v250, s5, 46
	s_and_b32 s5, s80, 31
	v_writelane_b32 v250, s5, 47
	s_ashr_i32 s5, s6, 31
	s_lshr_b32 s5, s5, 26
	s_add_i32 s5, s6, s5
	s_ashr_i32 s7, s5, 6
	v_writelane_b32 v250, s7, 48
	s_andn2_b32 s5, s5, 63
	v_writelane_b32 v250, s6, 49
	s_sub_i32 s5, s6, s5
	v_writelane_b32 v250, s5, 50
	s_lshl_b32 s5, s81, 1
	s_cmp_eq_u32 s2, 1
	v_writelane_b32 v250, s5, 51
	s_cselect_b64 s[6:7], -1, 0
	v_writelane_b32 v250, s6, 52
	s_cmp_eq_u32 s2, 2
	s_nop 0
	v_writelane_b32 v250, s7, 53
	s_cselect_b64 s[6:7], -1, 0
	v_writelane_b32 v250, s6, 54
	s_cmpk_lt_i32 s80, 0x100
	s_nop 0
	v_writelane_b32 v250, s7, 55
	s_cselect_b64 s[6:7], -1, 0
	v_writelane_b32 v250, s6, 56
	s_lshr_b32 s2, s13, 31
	s_bfe_i64 s[4:5], s[4:5], 0x100000
	v_writelane_b32 v250, s7, 57
	v_writelane_b32 v250, s13, 58
	v_writelane_b32 v250, s2, 59
	v_writelane_b32 v250, s14, 60
	s_lshl_b32 s2, s14, 19
	v_writelane_b32 v250, s2, 61
	s_lshl_b64 s[4:5], s[4:5], 19
	v_writelane_b32 v250, s4, 62
	s_add_i32 s2, s3, s12
	s_ashr_i32 s3, s2, 31
	v_writelane_b32 v250, s5, 63
	s_load_dwordx2 s[4:5], s[0:1], 0x0
	s_lshr_b32 s3, s3, 27
	s_add_i32 s3, s2, s3
	s_movk_i32 s13, 0x2400
	s_waitcnt lgkmcnt(0)
; __device__ __forceinline__ void conv_tokens(const Frame& F, int l, int wg0) {
;     const int gw = (F.bid - wg0) * NWAVES + F.wave, NGW = (F.G - wg0) * NWAVES, lane = F.lane;
;     const bf16* CV = (const bf16*)(F.ws + WS_CV); bf16* Y = (bf16*)(F.ws + WS_Y);
;     const float* cw = F.in[6] + (size_t)l * 3 * 256 + lane * 4;
;     const f32x4 w0 = *(const f32x4*)cw, w1 = *(const f32x4*)(cw + 256), w2 = *(const f32x4*)(cw + 512);
;     for (int tok0 = gw; tok0 < T; tok0 += 4 * NGW) {
; __device__ __forceinline__ void phase_prep(const Frame& F, int l) {
;     if (FAST_RET && FAST_NSA) {
;         const int first = F.G > 32 ? 16 : 0;
;         if (F.bid < first || first == 0) {
;             for (int u = F.bid; u < 16; u += F.G) { const int which = u >> 3, p0 = (u & 7) * 2, lw = l * 2 + which;
;                 RowCmp R{p0}; EpiCmp E{F.lds, (unsigned char*)F.ws, (const float*)(F.ws + WS_CB1) + lw * 128, (const bf16*)(F.ws + WS_CW2T) + (size_t)lw * 64 * 128, which, p0, F.wave};
;                 gemm_unit(F, (const bf16*)(F.ws + (which ? WS_NVC : WS_NKC)), R, (const bf16*)(F.ws + WS_CW1T) + (size_t)lw * 128 * 2048, E, 64, 2048); }
;             __syncthreads();
;         }
;         if (F.bid >= first) {
;             conv_tokens(F, l, first); for (int u = F.bid - first; u < NB * 4 * 16; u += F.G - first) ret_kv_unit(F, u); __syncthreads();
;             gates_tiles(F, l, first);
;             fp8_convert_range(F, l, F.bid - first, F.G - first, CONV_SPLIT);
	v_writelane_b32 v249, s4, 0
	s_nop 1
	v_writelane_b32 v249, s5, 1
	s_load_dwordx4 s[4:7], s[0:1], 0x28
	s_waitcnt lgkmcnt(0)
	v_writelane_b32 v249, s4, 2
	s_nop 1
	v_writelane_b32 v249, s5, 3
	v_writelane_b32 v249, s6, 4
	v_writelane_b32 v249, s7, 5
	s_load_dwordx2 s[4:5], s[0:1], 0x98
	s_waitcnt lgkmcnt(0)
	v_writelane_b32 v249, s4, 6
	s_nop 1
	v_writelane_b32 v249, s5, 7
	v_writelane_b32 v249, s16, 8
	s_ashr_i32 s4, s3, 5
	s_and_b32 s3, s3, 0xffe0
	v_writelane_b32 v249, s17, 9
	s_sub_i32 s3, s2, s3
	v_writelane_b32 v249, s18, 10
	s_bfe_i32 s2, s3, 0x80000
	v_writelane_b32 v249, s19, 11
	s_bfe_u32 s2, s2, 0x3000c
	v_writelane_b32 v249, s20, 12
	s_add_i32 s5, s3, s2
	v_writelane_b32 v249, s21, 13
	s_bfe_i32 s2, s5, 0x80000
	s_and_b32 s5, s5, 0xf8
	v_writelane_b32 v249, s22, 14
	s_sub_i32 s3, s3, s5
	v_writelane_b32 v249, s23, 15
	s_lshl_b32 s4, s4, 3
	s_sext_i32_i16 s6, s2
	s_sext_i32_i8 s3, s3
	v_writelane_b32 v249, s12, 16
	s_add_i32 s3, s4, s3
	s_ashr_i32 s4, s6, 3
	v_writelane_b32 v249, s4, 17
	s_lshr_b32 s2, s6, 3
	v_writelane_b32 v249, s3, 18
	s_lshl_b32 s3, s3, 19
	s_load_dwordx4 s[4:7], s[0:1], 0x60
	v_writelane_b32 v249, s3, 19
	s_bfe_i64 s[2:3], s[2:3], 0x100000
	s_lshl_b64 s[2:3], s[2:3], 19
	v_writelane_b32 v249, s2, 20
	s_lshl_b32 s0, s80, 1
	s_lshl_b32 s1, s10, 5
	v_writelane_b32 v249, s3, 21
	s_waitcnt lgkmcnt(0)
	v_writelane_b32 v249, s4, 22
	s_mul_i32 s2, s10, 24
	s_mov_b64 s[18:19], 0x80
	v_writelane_b32 v249, s5, 23
	v_writelane_b32 v249, s6, 24
	v_writelane_b32 v249, s7, 25
	v_writelane_b32 v249, s0, 26
	s_lshl_b32 s0, s10, 3
	s_sub_i32 s64, 0, s0
	s_lshl_b32 s0, s80, 3
	v_writelane_b32 v249, s0, 27
	s_lshl_b32 s0, s81, 5
	s_sub_i32 s65, s0, s1
	s_lshl_b32 s0, s81, 4
	s_sub_i32 s66, s0, s2
	s_mul_i32 s0, s81, 24
	s_sub_i32 s67, s0, s1
	s_lshl_b32 s0, s81, 3
	s_lshl_b32 s1, s10, 4
	s_sub_i32 s68, s0, s1
	s_lshl_b32 s0, s81, 7
	s_lshl_b32 s1, s80, 7
	s_sub_i32 s1, s0, s1
	s_add_i32 s1, s1, -16
	v_writelane_b32 v249, s1, 28
	s_lshl_b32 s1, s10, 7
	s_sub_i32 s69, s0, s1
	s_lshl_b32 s0, s80, 6
	v_writelane_b32 v249, s0, 29
	s_lshl_b32 s0, s81, 6
	v_writelane_b32 v249, s0, 30
	s_mov_b64 s[0:1], 0
	v_writelane_b32 v249, s0, 31
	s_mov_b32 s17, 0x3fb8aa3b
	s_mov_b32 s21, 0xc2ce8ed0
	v_writelane_b32 v249, s1, 32
	s_add_i32 s0, 0, 0x20020
	v_writelane_b32 v249, s0, 33
	s_add_i32 s0, 0, 0x20024
	v_writelane_b32 v249, s0, 34
	s_add_i32 s0, 0, 0x18800
	v_writelane_b32 v249, s0, 35
	s_add_i32 s0, 0, 0x19000
	v_writelane_b32 v249, s0, 36
	s_add_i32 s0, 0, 0x19800
	v_writelane_b32 v249, s0, 37
	s_add_i32 s0, 0, 0x20140
	v_writelane_b32 v249, s0, 38
	s_mov_b64 s[0:1], 0
	v_writelane_b32 v249, s0, 39
	s_mov_b32 s22, 0x42b17218
	s_mov_b32 s2, 0xf800000
	v_writelane_b32 v249, s1, 40
	s_mov_b32 s0, 0
	v_writelane_b32 v249, s0, 41
	v_writelane_b32 v249, s80, 42
	v_writelane_b32 v249, s81, 43
	v_writelane_b32 v249, s28, 44
	s_mov_b32 s12, 0xf149f2ca
	s_mov_b32 s16, 0x3fd744fd
	v_writelane_b32 v249, s29, 45
	v_writelane_b32 v249, s74, 46
	v_writelane_b32 v249, s75, 47
	v_writelane_b32 v249, s76, 48
	v_writelane_b32 v249, s64, 49
	v_writelane_b32 v249, s65, 50
	v_writelane_b32 v249, s66, 51
	v_writelane_b32 v249, s67, 52
	s_mov_b32 s20, 0x43600000
	s_mov_b32 s23, 0xc0e00000
	v_writelane_b32 v249, s68, 53
	v_writelane_b32 v249, s69, 54
	s_branch .LBB0_537

; __device__ __forceinline__ float w_qscale(float wmax) { return exp2f(floorf(log2f(128.f / fmaxf(wmax, 1e-30f)))); }
; __device__ __forceinline__ bool witem_decode(const Frame& F, int l, int it, WItem& t) {
;     constexpr int I_GU = 4 * 16, I_DN = 4 * 8, N_GU = NE * I_GU, N_DN = NE * I_DN;
;     const float* wmax = (const float*)((const unsigned*)(F.ws + WS_CTL) + CW_WMAX);
;     int r = it, nblk, item;
;     if (r < N_GU) { const int le = l * NE + r / I_GU; t.W = F.in[16] + (size_t)le * D * 2048; t.WT = (unsigned char*)(F.ws + WS_WGU) + (size_t)le * 2048 * D; t.N = 2048; t.map = 1; nblk = 16; item = r % I_GU; t.scale = w_qscale(wmax[l * 2 + 0]); }
;     else if ((r -= N_GU) < N_DN) { const int le = l * NE + r / I_DN; t.W = F.in[18] + (size_t)le * FF * D; t.WT = (unsigned char*)(F.ws + WS_WDN) + (size_t)le * D * FF; t.N = D; t.map = 3; nblk = 8; item = r % I_DN; t.scale = w_qscale(wmax[l * 2 + 1]); }
;     else return false;
;     t.k0 = 256 * (item / nblk); t.n0 = 128 * (item % nblk); return true;
; }
; __device__ __forceinline__ void witem_load(const WItem& t, int wave, int lane, f32x4 (&v)[16]) {
;     const float* wp = t.W + (size_t)(t.k0 + 32 * wave + 16 * (lane >> 5)) * t.N + t.n0 + 4 * (lane & 31);
; #pragma unroll
;     for (int q = 0; q < 16; ++q) v[q] = __builtin_nontemporal_load((const f32x4*)(wp + (size_t)q * t.N));
; __device__ __forceinline__ void fp8_convert_range(const Frame& F, int l, int start, int stride, int limit) {
;     __syncthreads();
;     WItem ta, tb; f32x4 va[16], vb[16];
;     int it = start;
;     bool ha = it < limit && witem_decode(F, l, it, ta);
;     if (ha) witem_load(ta, F.wave, F.lane, va);
.LBB0_1345:
	v_readlane_b32 s0, v250, 30
	v_readlane_b32 s1, v250, 31
	s_andn2_b64 vcc, exec, s[0:1]
	s_barrier
	s_cbranch_vccnz .LBB0_1354
	s_lshl_b32 s4, s96, 5
	v_readlane_b32 s0, v250, 32
	s_add_i32 s0, s4, s0
	s_ashr_i32 s1, s0, 31
	s_lshl_b64 s[6:7], s[0:1], 23
	s_lshl_b64 s[10:11], s[0:1], 21
	s_lshl_b64 s[0:1], s[28:29], 2
	s_add_u32 s0, s78, s0
	s_addc_u32 s1, s79, s1
	global_load_dword v1, v224, s[0:1]
	s_add_u32 s0, s0, 0x2000
	v_readlane_b32 s40, v249, 8
	s_addc_u32 s1, s1, 0
	v_readlane_b32 s42, v249, 10
	v_readlane_b32 s43, v249, 11
	s_add_u32 s26, s42, s6
	s_mov_b32 s9, 0x43000000
	s_addc_u32 s27, s43, s7
	s_add_u32 s3, s78, 0x38000000
	s_addc_u32 s5, s79, 0
	s_add_u32 s14, s3, s10
	s_addc_u32 s15, s5, s11
	v_lshrrev_b32_e32 v2, 1, v0
	s_waitcnt vmcnt(6)
	v_and_b32_e32 v54, 16, v2
	v_readlane_b32 s44, v249, 12
	v_readlane_b32 s45, v249, 13
	v_readlane_b32 s44, v250, 35
	s_waitcnt vmcnt(2)
	v_and_b32_e32 v130, 0x7c, v66
	v_readlane_b32 s45, v250, 36
	v_lshlrev_b32_e32 v198, 2, v130
	v_ashrrev_i32_e32 v131, 4, v0
	v_add_u32_e32 v134, 32, v131
	v_add_u32_e32 v135, 64, v131
	v_add_u32_e32 v136, 0x60, v131
	v_lshrrev_b32_e32 v56, 2, v136
	v_and_b32_e32 v57, 0x63, v136
	s_waitcnt vmcnt(1)
	v_mov_b32_e32 v133, v199
	v_readlane_b32 s41, v249, 9
	v_readlane_b32 s46, v249, 14
	v_readlane_b32 s47, v249, 15
	s_waitcnt vmcnt(0)
	v_max_f32_e32 v1, v1, v1
	v_max_f32_e32 v1, 0xda24260, v1
	v_div_scale_f32 v3, s[6:7], v1, v1, s9
	v_rcp_f32_e32 v4, v3
	v_div_scale_f32 v5, vcc, s9, v1, s9
	s_mov_b32 s6, 0x800000
	v_fma_f32 v6, -v3, v4, 1.0
	v_fmac_f32_e32 v4, v6, v4
	v_mul_f32_e32 v6, v5, v4
	v_fma_f32 v7, -v3, v6, v5
	v_fmac_f32_e32 v6, v7, v4
	v_fma_f32 v3, -v3, v6, v5
	v_div_fmas_f32 v3, v3, v4, v6
	v_div_fixup_f32 v1, v3, v1, s9
	v_cmp_gt_f32_e32 vcc, s6, v1
	s_and_b64 s[6:7], vcc, exec
	s_cselect_b32 s6, 32, 0
	v_ldexp_f32 v1, v1, s6
	v_log_f32_e32 v1, v1
	v_cndmask_b32_e32 v3, 0, v232, vcc
	s_mov_b32 s6, 0xc2fc0000
	v_readlane_b32 s9, v250, 34
	v_sub_f32_e32 v1, v1, v3
	v_floor_f32_e32 v1, v1
	v_cmp_gt_f32_e32 vcc, s6, v1
	s_and_b64 s[6:7], vcc, exec
	s_cselect_b32 s7, 0xffffffc0, 0
	s_lshl_b32 s6, s8, 5
	s_add_i32 s8, s6, s9
	v_or_b32_e32 v2, s8, v54
	v_ashrrev_i32_e32 v3, 31, v2
	v_lshlrev_b64 v[2:3], 13, v[2:3]
	v_lshl_add_u64 v[2:3], s[26:27], 0, v[2:3]
	v_lshl_add_u64 v[2:3], s[44:45], 2, v[2:3]
	v_lshl_add_u64 v[38:39], v[2:3], 0, v[198:199]
	v_cndmask_b32_e32 v55, 0, v233, vcc
	v_add_co_u32_e32 v6, vcc, s70, v38
	s_movk_i32 s8, 0x4000
	s_nop 0
	v_addc_co_u32_e32 v7, vcc, 0, v39, vcc
	v_add_co_u32_e32 v10, vcc, s8, v38
	s_movk_i32 s8, 0x6000
	s_nop 0
	v_addc_co_u32_e32 v11, vcc, 0, v39, vcc
	v_add_co_u32_e32 v14, vcc, s8, v38
	s_mov_b32 s8, 0x8000
	s_nop 0
	v_addc_co_u32_e32 v15, vcc, 0, v39, vcc
	v_add_co_u32_e32 v18, vcc, s8, v38
	s_mov_b32 s8, 0xa000
	s_nop 0
	v_addc_co_u32_e32 v19, vcc, 0, v39, vcc
	v_add_co_u32_e32 v22, vcc, s8, v38
	s_mov_b32 s8, 0xc000
	s_nop 0
	v_addc_co_u32_e32 v23, vcc, 0, v39, vcc
	v_add_co_u32_e32 v26, vcc, s8, v38
	s_mov_b32 s8, 0xe000
	s_nop 0
	v_addc_co_u32_e32 v27, vcc, 0, v39, vcc
	v_add_co_u32_e32 v30, vcc, s8, v38
	s_mov_b32 s8, 0x12000
	s_nop 0
	v_addc_co_u32_e32 v31, vcc, 0, v39, vcc
	v_add_co_u32_e32 v34, vcc, s71, v38
	v_add_f32_e32 v1, v1, v55
	s_nop 0
	v_addc_co_u32_e32 v35, vcc, 0, v39, vcc
	v_add_co_u32_e32 v40, vcc, s8, v38
	s_mov_b32 s8, 0x14000
	s_nop 0
	v_addc_co_u32_e32 v41, vcc, 0, v39, vcc
	v_add_co_u32_e32 v42, vcc, s8, v38
	s_mov_b32 s8, 0x16000
	s_nop 0
	v_addc_co_u32_e32 v43, vcc, 0, v39, vcc
	v_add_co_u32_e32 v44, vcc, s8, v38
	s_mov_b32 s8, 0x18000
	s_nop 0
	v_addc_co_u32_e32 v45, vcc, 0, v39, vcc
	v_add_co_u32_e32 v46, vcc, s8, v38
	s_mov_b32 s8, 0x1a000
	s_nop 0
	v_addc_co_u32_e32 v47, vcc, 0, v39, vcc
	v_add_co_u32_e32 v48, vcc, s8, v38
	s_mov_b32 s8, 0x1c000
	s_nop 0
	v_addc_co_u32_e32 v49, vcc, 0, v39, vcc
	global_load_dwordx4 v[2:5], v[38:39], off nt
	s_nop 0
	global_load_dwordx4 v[6:9], v[6:7], off nt
	s_nop 0
	global_load_dwordx4 v[10:13], v[10:11], off nt
	s_nop 0
	global_load_dwordx4 v[14:17], v[14:15], off nt
	s_nop 0
	global_load_dwordx4 v[18:21], v[18:19], off nt
	s_nop 0
	global_load_dwordx4 v[22:25], v[22:23], off nt
	s_nop 0
	global_load_dwordx4 v[26:29], v[26:27], off nt
	s_nop 0
	global_load_dwordx4 v[30:33], v[30:31], off nt
	s_nop 0
	global_load_dwordx4 v[34:37], v[34:35], off nt
	s_nop 0
	global_load_dwordx4 v[50:53], v[40:41], off nt
	global_load_dwordx4 v[62:65], v[42:43], off nt
	global_load_dwordx4 v[70:73], v[44:45], off nt
	global_load_dwordx4 v[82:85], v[46:47], off nt
	global_load_dwordx4 v[86:89], v[48:49], off nt
	v_add_co_u32_e32 v40, vcc, s8, v38
	s_mov_b32 s8, 0x1e000
	s_nop 0
	v_addc_co_u32_e32 v41, vcc, 0, v39, vcc
	v_add_co_u32_e32 v38, vcc, s8, v38
	v_exp_f32_e32 v1, v1
	s_nop 0
	v_addc_co_u32_e32 v39, vcc, 0, v39, vcc
	global_load_dwordx4 v[94:97], v[40:41], off nt
	global_load_dwordx4 v[102:105], v[38:39], off nt
	v_ldexp_f32 v146, v1, s7
	v_or_b32_e32 v1, s6, v54
	s_add_i32 s6, s6, 0
	v_and_b32_e32 v38, 31, v0
	v_mov_b32_e32 v39, s6
	s_movk_i32 s6, 0x110
	v_lshlrev_b32_e32 v40, 5, v131
	v_mad_u32_u24 v38, v38, s6, v39
	v_lshlrev_b32_e32 v39, 4, v0
	v_and_b32_e32 v40, 0x60, v40
	v_ashrrev_i32_e32 v41, 6, v0
	v_lshrrev_b32_e32 v45, 2, v134
	v_lshrrev_b32_e32 v48, 2, v135
	v_and_b32_e32 v132, 0xf0, v39
	v_add_u32_e32 v41, v40, v41
	v_lshlrev_b32_e32 v42, 2, v131
	v_lshrrev_b32_e32 v43, 1, v131
	v_add_u32_e32 v45, v40, v45
	v_lshlrev_b32_e32 v46, 2, v134
	v_add_u32_e32 v48, v40, v48
	v_lshlrev_b32_e32 v49, 2, v135
	v_add_u32_e32 v40, v40, v56
	v_lshlrev_b32_e32 v56, 2, v136
	v_add_u32_e32 v39, 0, v132
	v_mul_lo_u32 v41, v41, s6
	v_and_b32_e32 v42, 16, v42
	v_and_b32_e32 v43, 12, v43
	v_and_b32_e32 v44, 0x63, v131
	v_mul_lo_u32 v45, v45, s6
	v_and_b32_e32 v46, 16, v46
	v_and_b32_e32 v47, 0x63, v134
	v_mul_lo_u32 v48, v48, s6
	v_and_b32_e32 v49, 16, v49
	v_and_b32_e32 v55, 0x63, v135
	v_mul_lo_u32 v40, v40, s6
	v_and_b32_e32 v56, 16, v56
	v_or3_b32 v137, v42, v44, v43
	v_or3_b32 v138, v47, v46, v43
	v_or3_b32 v139, v55, v49, v43
	v_or3_b32 v140, v57, v56, v43
	v_add_u32_e32 v141, v38, v54
	v_add_u32_e32 v142, v39, v41
	v_add_u32_e32 v143, v39, v45
	v_add_u32_e32 v144, v39, v48
	v_add_u32_e32 v145, v39, v40
	v_readlane_b32 s6, v248, 40
	s_mov_b32 s42, s9
	s_branch .LBB0_1348
